# both attention loops: DMA pointer increments deferred from before the loop barrier to after the first K-fragment reads
# baseline (speedup 1.0000x reference)
; #define LAS __attribute__((address_space(3)))
; #define WAIT_BAR() asm volatile("s_waitcnt vmcnt(0) lgkmcnt(0)\n\ts_barrier" ::: "memory")
; #define BMODE(t) do { if constexpr (DIFF) { const int dd = (t) * 64 - qw; float cbn; if (dd <= -191) { bm = 1; cbn = bL; } else if (dd >= 159) { bm = 1; cbn = bR; } else { bm = 2; cbn = 0.f; } \
;             ix = dd - r32 + 256 + 4 * hi; if (cbn != cb) { cb = cbn; moved = true; } } } while (0)
; #define NEGM() do { if (moved) { const float v_ = cb - m_reg; _Pragma("unroll") for (int r = 0; r < 16; ++r) negm[r] = v_; asm volatile("" : "+v"(negm)); } } while (0)
; #define WAIT_BAR() asm volatile("s_waitcnt vmcnt(0) lgkmcnt(0)\n\ts_barrier" ::: "memory")
; #define MFMA32(a, b, c) __builtin_amdgcn_mfma_f32_32x32x16_bf16(a, b, c, 0, 0, 0)
; #define BMODE(t) do { if constexpr (DIFF) { const int dd = (t) * 64 - qw; float cbn; if (dd <= -191) { bm = 1; cbn = bL; } else if (dd >= 159) { bm = 1; cbn = bR; } else { bm = 2; cbn = 0.f; } \
;             ix = dd - r32 + 256 + 4 * hi; if (cbn != cb) { cb = cbn; moved = true; } } } while (0)
; template <int NCB, bool DIFF, bool STAT>
; __device__ __forceinline__ void attn_unit(LAS char* lds, const Params& P, int s, int head, int qb, float sref) {
;     ...
;         f32x16 negm;
; #pragma unroll
;         for (int d = 0; d < NCB; ++d) o[d] = f32x16{};
;         f32x16 pA0, pA1, pB0, pB1; float alA = 1.f, alB = 1.f;
;         u32x4 pw[4];
;         int bm = 0, ix = 0;
;         WAIT_BAR();
;         BMODE(0); NEGM();
;         { const LAS char* kp_ = kp0;
; #pragma unroll
;           for (int d0 = 0; d0 < 4; ++d0) { const bf16x8 b0 = *(const LAS bf16x8*)(kp_ + d0 * 2048), b1 = *(const LAS bf16x8*)(kp_ + d0 * 2048 + 512);
;               if (d0 == 0) { if constexpr (ZREF) { pA0 = MFMA32(b0, qr[0], f32x16{}); pA1 = MFMA32(b1, qr[0], f32x16{}); } else { pA0 = MFMA32(b0, qr[0], negm); pA1 = MFMA32(b1, qr[0], negm); } } else { pA0 = MFMA32(b0, qr[d0], pA0); pA1 = MFMA32(b1, qr[d0], pA1); } } }
;         bias_add<DIFF>(pA0, pA1, bm, tab, ix);
;         if constexpr (!STAT) rowmax_decide<DIFF, true>(pA0, pA1, m_reg, alA, moved, bm, tab, ix); else moved = false;
; #pragma unroll
;         for (int r = 0; r < 16; ++r) { pA0[r] = __builtin_amdgcn_exp2f(pA0[r]); pA1[r] = __builtin_amdgcn_exp2f(pA1[r]); }
;         int sl_prev = 0, sl_cur = 1;
;         bf16x8 kf[3];
.LBB0_511:
	s_nop 10
	v_exp_f32_e32 v82, v18
	v_exp_f32_e32 v83, v19
	v_exp_f32_e32 v84, v20
	v_exp_f32_e32 v85, v21
	v_exp_f32_e32 v86, v22
	v_exp_f32_e32 v87, v23
	v_exp_f32_e32 v88, v24
	v_exp_f32_e32 v89, v25
	v_exp_f32_e32 v90, v26
	v_exp_f32_e32 v91, v27
	v_exp_f32_e32 v92, v28
	v_exp_f32_e32 v93, v29
	v_exp_f32_e32 v94, v30
	v_exp_f32_e32 v95, v31
	v_exp_f32_e32 v96, v32
	v_exp_f32_e32 v97, v33
	v_exp_f32_e32 v98, v2
	v_exp_f32_e32 v99, v3
	v_exp_f32_e32 v100, v4
	v_exp_f32_e32 v101, v5
	v_exp_f32_e32 v102, v6
	v_exp_f32_e32 v103, v7
	v_exp_f32_e32 v104, v8
	v_exp_f32_e32 v105, v9
	v_exp_f32_e32 v106, v10
	v_exp_f32_e32 v107, v11
	v_exp_f32_e32 v108, v12
	v_exp_f32_e32 v109, v13
	v_exp_f32_e32 v110, v14
	v_exp_f32_e32 v111, v15
	v_exp_f32_e32 v112, v16
	v_exp_f32_e32 v113, v17
	s_xor_b64 s[42:43], s[46:47], -1
	s_add_u32 s46, s40, 0x8000
	v_mov_b32_e32 v216, 0
	v_mov_b32_e32 v240, 0
	v_mov_b32_e32 v241, 0
	v_mov_b32_e32 v242, 0
	v_mov_b32_e32 v243, 0
	v_and_b32_e32 v236, 15, v230
	v_bfe_u32 v237, v230, 4, 1
	v_mov_b32_e32 v238, 0x3f803f80
	v_cmp_eq_u32_e64 s[98:99], v236, v237
	s_nop 1
	v_cndmask_b32_e64 v236, 0, v238, s[98:99]
	v_mov_b32_e32 v237, v236
	v_mov_b32_e32 v238, v236
	v_mov_b32_e32 v239, v236
	s_addc_u32 s47, s41, 0
	s_mov_b32 s14, 1
	s_mov_b32 s9, 0
	s_mov_b32 s67, 4
	s_mov_b64 s[40:41], s[48:49]
	s_mov_b32 s66, s8
	v_mov_b32_e32 v218, v215
	v_mov_b32_e32 v166, v209
	v_mov_b32_e32 v50, 0
	v_mov_b32_e32 v51, v216
	v_mov_b32_e32 v52, v216
	v_mov_b32_e32 v53, v216
	v_mov_b32_e32 v54, v216
	v_mov_b32_e32 v55, v216
	v_mov_b32_e32 v56, v216
	v_mov_b32_e32 v57, v216
	v_mov_b32_e32 v58, v216
	v_mov_b32_e32 v59, v216
	v_mov_b32_e32 v60, v216
	v_mov_b32_e32 v61, v216
	v_mov_b32_e32 v62, v216
	v_mov_b32_e32 v63, v216
	v_mov_b32_e32 v64, v216
	v_mov_b32_e32 v65, v216
	v_mov_b32_e32 v66, 0
	v_mov_b32_e32 v67, v216
	v_mov_b32_e32 v68, v216
	v_mov_b32_e32 v69, v216
	v_mov_b32_e32 v70, v216
	v_mov_b32_e32 v71, v216
	v_mov_b32_e32 v72, v216
	v_mov_b32_e32 v73, v216
	v_mov_b32_e32 v74, v216
	v_mov_b32_e32 v75, v216
	v_mov_b32_e32 v76, v216
	v_mov_b32_e32 v77, v216
	v_mov_b32_e32 v78, v216
	v_mov_b32_e32 v79, v216
	v_mov_b32_e32 v80, v216
	v_mov_b32_e32 v81, v216
	v_mov_b32_e32 v2, 0
	v_mov_b32_e32 v3, v216
	v_mov_b32_e32 v4, v216
	v_mov_b32_e32 v5, v216
	v_mov_b32_e32 v6, v216
	v_mov_b32_e32 v7, v216
	v_mov_b32_e32 v8, v216
	v_mov_b32_e32 v9, v216
	v_mov_b32_e32 v10, v216
	v_mov_b32_e32 v11, v216
	v_mov_b32_e32 v12, v216
	v_mov_b32_e32 v13, v216
	v_mov_b32_e32 v14, v216
	v_mov_b32_e32 v15, v216
	v_mov_b32_e32 v16, v216
	v_mov_b32_e32 v17, v216
	v_mov_b32_e32 v18, 0
	v_mov_b32_e32 v19, v216
	v_mov_b32_e32 v20, v216
	v_mov_b32_e32 v21, v216
	v_mov_b32_e32 v22, v216
	v_mov_b32_e32 v23, v216
	v_mov_b32_e32 v24, v216
	v_mov_b32_e32 v25, v216
	v_mov_b32_e32 v26, v216
	v_mov_b32_e32 v27, v216
	v_mov_b32_e32 v28, v216
	v_mov_b32_e32 v29, v216
	v_mov_b32_e32 v30, v216
	v_mov_b32_e32 v31, v216
	v_mov_b32_e32 v32, v216
	v_mov_b32_e32 v33, v216
	v_lshl_add_u32 v169, s14, 13, v205
	ds_read_b128 v[114:117], v169
	ds_read_b128 v[220:223], v169 offset:512
	s_branch .Ldiff_after_reads
.LBB0_512:
	s_waitcnt lgkmcnt(2)
	v_mfma_f32_32x32x16_bf16 v[50:65], v[162:165], v[122:125], v[50:65]
	ds_read_b64_tr_b16 v[126:127], v222 offset:1024
	ds_read_b64_tr_b16 v[128:129], v222 offset:3072
	v_mfma_f32_16x16x32_bf16 v[240:243], v[114:117], v[236:239], v[240:243]
	v_cndmask_b32_e64 v166, v221, v223, s[4:5]
	v_exp_f32_e32 v98, v98
	v_exp_f32_e32 v99, v99
	s_waitcnt lgkmcnt(2)
	v_mfma_f32_32x32x16_bf16 v[66:81], v[162:165], v[118:121], v[66:81]
	ds_read_b64_tr_b16 v[122:123], v222 offset:1536
	ds_read_b64_tr_b16 v[124:125], v222 offset:3584
	v_exp_f32_e32 v100, v100
	v_exp_f32_e32 v101, v101
	s_waitcnt lgkmcnt(2)
	v_mfma_f32_32x32x16_bf16 v[2:17], v[162:165], v[126:129], v[2:17]
	ds_read_b64_tr_b16 v[118:119], v222 offset:4096
	ds_read_b64_tr_b16 v[120:121], v222 offset:6144
	v_exp_f32_e32 v102, v102
	v_exp_f32_e32 v103, v103
	s_waitcnt lgkmcnt(2)
	v_mfma_f32_32x32x16_bf16 v[18:33], v[162:165], v[122:125], v[18:33]
	ds_read_b64_tr_b16 v[126:127], v222 offset:4608
	ds_read_b64_tr_b16 v[128:129], v222 offset:6656
	v_exp_f32_e32 v104, v104
	v_exp_f32_e32 v105, v105
	s_waitcnt lgkmcnt(2)
	v_mfma_f32_32x32x16_bf16 v[50:65], v[134:137], v[118:121], v[50:65]
	ds_read_b64_tr_b16 v[122:123], v222 offset:5120
	ds_read_b64_tr_b16 v[124:125], v222 offset:7168
	v_exp_f32_e32 v106, v106
	v_exp_f32_e32 v107, v107
	s_waitcnt lgkmcnt(2)
	v_mfma_f32_32x32x16_bf16 v[66:81], v[134:137], v[126:129], v[66:81]
	ds_read_b64_tr_b16 v[118:119], v222 offset:5632
	ds_read_b64_tr_b16 v[120:121], v222 offset:7680
	v_exp_f32_e32 v108, v108
	v_exp_f32_e32 v109, v109
	s_waitcnt lgkmcnt(2)
	v_mfma_f32_32x32x16_bf16 v[2:17], v[134:137], v[122:125], v[2:17]
	ds_read_b64_tr_b16 v[126:127], v222 offset:8192
	ds_read_b64_tr_b16 v[128:129], v222 offset:10240
	v_exp_f32_e32 v110, v110
	v_exp_f32_e32 v111, v111
	s_waitcnt lgkmcnt(2)
	v_mfma_f32_32x32x16_bf16 v[18:33], v[134:137], v[118:121], v[18:33]
	ds_read_b64_tr_b16 v[122:123], v222 offset:8704
	ds_read_b64_tr_b16 v[124:125], v222 offset:10752
	v_exp_f32_e32 v112, v112
	v_exp_f32_e32 v113, v113
	s_waitcnt lgkmcnt(2)
	v_mfma_f32_32x32x16_bf16 v[50:65], v[130:133], v[126:129], v[50:65]
	ds_read_b64_tr_b16 v[118:119], v222 offset:9216
	ds_read_b64_tr_b16 v[120:121], v222 offset:11264
	v_exp_f32_e32 v82, v82
	v_exp_f32_e32 v83, v83
	s_waitcnt lgkmcnt(2)
	v_mfma_f32_32x32x16_bf16 v[66:81], v[130:133], v[122:125], v[66:81]
	ds_read_b64_tr_b16 v[126:127], v222 offset:9728
	ds_read_b64_tr_b16 v[128:129], v222 offset:11776
	v_exp_f32_e32 v84, v84
	v_exp_f32_e32 v85, v85
	s_waitcnt lgkmcnt(2)
	v_mfma_f32_32x32x16_bf16 v[2:17], v[130:133], v[118:121], v[2:17]
	ds_read_b64_tr_b16 v[122:123], v222 offset:12288
	ds_read_b64_tr_b16 v[124:125], v222 offset:14336
	v_exp_f32_e32 v86, v86
	v_exp_f32_e32 v87, v87
	s_waitcnt lgkmcnt(2)
	v_mfma_f32_32x32x16_bf16 v[18:33], v[130:133], v[126:129], v[18:33]
	ds_read_b64_tr_b16 v[118:119], v222 offset:12800
	ds_read_b64_tr_b16 v[120:121], v222 offset:14848
	v_exp_f32_e32 v88, v88
	v_exp_f32_e32 v89, v89
	s_waitcnt lgkmcnt(2)
	v_mfma_f32_32x32x16_bf16 v[50:65], v[114:117], v[122:125], v[50:65]
	ds_read_b64_tr_b16 v[126:127], v222 offset:13312
	ds_read_b64_tr_b16 v[128:129], v222 offset:15360
	v_exp_f32_e32 v90, v90
	v_exp_f32_e32 v91, v91
	s_waitcnt lgkmcnt(2)
	v_mfma_f32_32x32x16_bf16 v[66:81], v[114:117], v[118:121], v[66:81]
	ds_read_b64_tr_b16 v[122:123], v222 offset:13824
	ds_read_b64_tr_b16 v[124:125], v222 offset:15872
	v_exp_f32_e32 v92, v92
	v_exp_f32_e32 v93, v93
	s_waitcnt lgkmcnt(2)
	v_mfma_f32_32x32x16_bf16 v[2:17], v[114:117], v[126:129], v[2:17]
	v_exp_f32_e32 v94, v94
	v_exp_f32_e32 v95, v95
	s_waitcnt lgkmcnt(0)
	v_mfma_f32_32x32x16_bf16 v[18:33], v[114:117], v[122:125], v[18:33]
	v_exp_f32_e32 v96, v96
	v_exp_f32_e32 v97, v97
	s_add_i32 s4, s9, 1
	s_cmp_lg_u32 s9, 4
	s_cselect_b32 s14, s4, 0
	s_add_i32 s67, s67, 2
	s_addk_i32 s66, 0x80
	v_add_u32_e32 v218, 0x200, v218
	s_and_b64 vcc, exec, s[50:51]
	s_waitcnt vmcnt(0) lgkmcnt(0)
	s_barrier
	s_cbranch_vccnz .LBB0_525
.LBB0_513:
	v_lshl_add_u32 v169, s14, 13, v205
	ds_read_b128 v[114:117], v169
	ds_read_b128 v[220:223], v169 offset:512
	s_add_u32 s40, s40, 0x8000
	s_addc_u32 s41, s41, 0
	s_add_u32 s46, s46, 0x4000
	s_addc_u32 s47, s47, 0
.Ldiff_after_reads:
	s_add_i32 s4, s66, 0xffffff02
	s_cmpk_lt_i32 s4, 0xff42
	s_cselect_b64 vcc, -1, 0
	s_cmpk_gt_i32 s4, 0x9e
	s_cselect_b64 s[4:5], -1, 0
	v_cndmask_b32_e64 v253, 0, v207, s[4:5]
	v_cndmask_b32_e32 v168, v253, v206, vcc
	v_cmp_eq_f32_e32 vcc, v168, v166
	v_cmp_neq_f32_e64 s[4:5], v168, v166
	s_cbranch_vccnz .LBB0_515
	v_sub_f32_e32 v34, v168, v217
	v_mov_b32_e32 v35, v34
	v_mov_b32_e32 v36, v34
	v_mov_b32_e32 v37, v34
	v_mov_b32_e32 v38, v34
	v_mov_b32_e32 v39, v34
	v_mov_b32_e32 v40, v34
	v_mov_b32_e32 v41, v34
	v_mov_b32_e32 v42, v34
	v_mov_b32_e32 v43, v34
	v_mov_b32_e32 v44, v34
	v_mov_b32_e32 v45, v34
	v_mov_b32_e32 v46, v34
	v_mov_b32_e32 v47, v34
	v_mov_b32_e32 v48, v34
	v_mov_b32_e32 v49, v34
